# P6 tasks dealt wave-major so all 256 CUs take part (6 waves each) instead of 198 CUs with 8
# speedup vs baseline: 1.0016x; 1.0016x over previous
.LBB0_996:
	s_or_b64 exec, exec, s[0:1]
	v_readlane_b32 s0, v239, 2
	s_waitcnt lgkmcnt(0)
	v_mov_b32_e32 v0, v176
	s_barrier
	s_lshl_b32 s22, s0, 9
	s_mov_b32 s0, 0x18c00
	v_lshrrev_b32_e32 v144, 6, v0
	s_lshr_b32 s4, s22, 3
	v_mul_lo_u32 v144, v144, s4
	s_lshr_b32 s5, s96, 3
	v_and_b32_e32 v145, 63, v0
	v_add3_u32 v144, v144, s5, v145
	v_readlane_b32 s1, v239, 3
	v_cmp_gt_i32_e32 vcc, s0, v144
	s_and_saveexec_b64 s[0:1], vcc
	s_cbranch_execz .LBB0_1005
	s_add_u32 s8, s58, 0x5800
	s_addc_u32 s9, s59, 0
	s_add_u32 s10, s56, 0x5800
	s_addc_u32 s11, s57, 0
	s_add_u32 s12, s56, 0xb000
	s_addc_u32 s13, s57, 0
	s_add_u32 s14, s56, 0x10800
	s_addc_u32 s15, s57, 0
	s_add_u32 s16, s56, 0x16000
	s_addc_u32 s17, s57, 0
	s_add_u32 s18, s56, 0x1b800
	s_addc_u32 s19, s57, 0
	s_mov_b64 s[20:21], 0
	s_mov_b32 s23, 0x16000
	s_movk_i32 s24, 0x5800
	s_movk_i32 s25, 0x5000
	s_mov_b32 s26, 0xb000
	s_mov_b32 s27, 0x10000
	v_mov_b32_e32 v145, v144
	s_branch .LBB0_999
